# combine phase rewritten by hand: per-lane norm/conv constants hoisted out of the token loop, all 14 row loads of a token issued together, two tokens in flight with counted vmcnt (was ~22 dependent rou
# speedup vs baseline: 1.0422x; 1.0216x over previous
.LBB0_479:
	s_andn2_b64 vcc, exec, s[0:1]
	s_cbranch_vccnz .LBB0_550
	s_mov_b64 s[0:1], s[88:89]
	v_mov_b32_e32 v0, v194
	v_readlane_b32 s5, v252, 0
	v_readfirstlane_b32 s4, v0
	s_ashr_i32 s4, s4, 6
	s_add_i32 s16, s4, s5
	s_cmpk_gt_i32 s16, 0x2fff
	s_cbranch_scc1 .LBB0_499
	s_load_dwordx4 s[4:7], s[0:1], 0x58
	s_load_dwordx2 s[14:15], s[0:1], 0x90
	v_and_b32_e32 v0, 63, v194
	v_lshlrev_b32_e32 v1, 6, v0
	v_xor_b32_e32 v9, 1, v0
	v_xor_b32_e32 v10, 2, v0
	v_xor_b32_e32 v11, 4, v0
	v_lshlrev_b32_e32 v9, 2, v9
	v_lshlrev_b32_e32 v10, 2, v10
	v_lshlrev_b32_e32 v11, 2, v11
	v_lshlrev_b32_e32 v0, 5, v0
	v_add_u32_e32 v3, 0x2000, v0
	v_add_u32_e32 v4, 0x2800, v0
	v_add_u32_e32 v5, 0x3000, v0
	s_lshl_b32 s20, s80, 12
	s_mul_i32 s21, s80, 0x3000
	s_waitcnt lgkmcnt(0)
	s_add_u32 s4, s4, s20
	s_addc_u32 s5, s5, 0
	s_add_u32 s6, s6, s21
	s_addc_u32 s7, s7, 0
	s_add_u32 s22, s6, 0x1000
	s_addc_u32 s23, s7, 0
	s_add_u32 s24, s6, 0x2000
	s_addc_u32 s25, s7, 0
	global_load_dwordx4 v[16:19], v1, s[4:5]
	global_load_dwordx4 v[20:23], v1, s[4:5] offset:16
	global_load_dwordx4 v[24:27], v1, s[4:5] offset:32
	global_load_dwordx4 v[28:31], v1, s[4:5] offset:48
	global_load_dwordx4 v[32:35], v1, s[6:7]
	global_load_dwordx4 v[36:39], v1, s[6:7] offset:16
	global_load_dwordx4 v[40:43], v1, s[6:7] offset:32
	global_load_dwordx4 v[44:47], v1, s[6:7] offset:48
	global_load_dwordx4 v[48:51], v1, s[22:23]
	global_load_dwordx4 v[52:55], v1, s[22:23] offset:16
	global_load_dwordx4 v[56:59], v1, s[22:23] offset:32
	global_load_dwordx4 v[60:63], v1, s[22:23] offset:48
	global_load_dwordx4 v[64:67], v1, s[24:25]
	global_load_dwordx4 v[68:71], v1, s[24:25] offset:16
	global_load_dwordx4 v[72:75], v1, s[24:25] offset:32
	global_load_dwordx4 v[76:79], v1, s[24:25] offset:48
	s_and_b32 s20, s80, 1
	s_cmp_lg_u32 s20, 0
	s_cselect_b32 s20, 0xfff, 63
	s_cselect_b32 s21, 64, 1
	s_ashr_i32 s17, s16, 31
	s_lshl_b64 s[22:23], s[16:17], 11
	s_add_u32 s38, s14, s22
	s_addc_u32 s39, s15, s23
	s_add_u32 s38, s38, 0x22000000
	s_addc_u32 s39, s39, 0
	s_add_u32 s40, s38, 0x1800000
	s_addc_u32 s41, s39, 0
	s_lshl_b64 s[22:23], s[16:17], 14
	s_add_u32 s34, s14, s22
	s_addc_u32 s35, s15, s23
	s_add_u32 s34, s34, 0x16000000
	s_addc_u32 s35, s35, 0
	s_lshl_b64 s[22:23], s[16:17], 12
	s_add_u32 s24, s14, s22
	s_addc_u32 s25, s15, s23
	s_add_u32 s24, s24, 0x13000000
	s_addc_u32 s25, s25, 0
	s_cmpk_lt_i32 s16, 0x1000
	s_cselect_b32 s22, 0xff, s20
	s_cselect_b32 s23, 1, s21
	s_and_b32 s30, s16, s22
	s_lshl_b32 s17, s23, 14
	s_cmp_ge_u32 s30, s23
	s_cselect_b32 s42, s17, 0
	s_cselect_b32 s14, 1, 0
	s_add_i32 s30, s30, s23
	s_cmp_le_u32 s30, s22
	s_cselect_b32 s30, s17, 0
	s_cselect_b32 s15, 1, 0
	s_sub_u32 s42, s34, s42
	s_subb_u32 s43, s35, 0
	s_add_u32 s22, s34, s30
	s_addc_u32 s23, s35, 0
	global_load_dwordx4 v[80:83], v0, s[38:39]
	global_load_dwordx4 v[84:87], v0, s[38:39] offset:16
	global_load_dwordx4 v[88:91], v0, s[40:41]
	global_load_dwordx4 v[92:95], v0, s[40:41] offset:16
	global_load_dwordx4 v[96:99], v3, s[34:35]
	global_load_dwordx4 v[100:103], v3, s[34:35] offset:16
	global_load_dwordx4 v[104:107], v4, s[34:35]
	global_load_dwordx4 v[108:111], v4, s[34:35] offset:16
	global_load_dwordx4 v[112:115], v5, s[34:35]
	global_load_dwordx4 v[116:119], v5, s[34:35] offset:16
	global_load_dwordx4 v[120:123], v5, s[42:43]
	global_load_dwordx4 v[124:127], v5, s[42:43] offset:16
	global_load_dwordx4 v[128:131], v5, s[22:23]
	global_load_dwordx4 v[132:135], v5, s[22:23] offset:16
	v_readlane_b32 s6, v253, 41
.Lcb_loop:
	s_add_i32 s16, s16, s6
	s_cmpk_lt_i32 s16, 0x3000
	s_cbranch_scc0 .Lcb_last_a
	s_add_u32 s38, s38, s28
	s_addc_u32 s39, s39, s29
	s_add_u32 s40, s40, s28
	s_addc_u32 s41, s41, s29
	s_add_u32 s34, s34, s36
	s_addc_u32 s35, s35, s37
	s_cmpk_lt_i32 s16, 0x1000
	s_cselect_b32 s22, 0xff, s20
	s_cselect_b32 s23, 1, s21
	s_and_b32 s30, s16, s22
	s_lshl_b32 s17, s23, 14
	s_cmp_ge_u32 s30, s23
	s_cselect_b32 s42, s17, 0
	s_cselect_b32 s4, 1, 0
	s_add_i32 s30, s30, s23
	s_cmp_le_u32 s30, s22
	s_cselect_b32 s30, s17, 0
	s_cselect_b32 s5, 1, 0
	s_sub_u32 s42, s34, s42
	s_subb_u32 s43, s35, 0
	s_add_u32 s22, s34, s30
	s_addc_u32 s23, s35, 0
	global_load_dwordx4 v[136:139], v0, s[38:39]
	global_load_dwordx4 v[140:143], v0, s[38:39] offset:16
	global_load_dwordx4 v[144:147], v0, s[40:41]
	global_load_dwordx4 v[148:151], v0, s[40:41] offset:16
	global_load_dwordx4 v[162:165], v3, s[34:35]
	global_load_dwordx4 v[166:169], v3, s[34:35] offset:16
	global_load_dwordx4 v[170:173], v4, s[34:35]
	global_load_dwordx4 v[174:177], v4, s[34:35] offset:16
	global_load_dwordx4 v[178:181], v5, s[34:35]
	global_load_dwordx4 v[182:185], v5, s[34:35] offset:16
	global_load_dwordx4 v[186:189], v5, s[42:43]
	global_load_dwordx4 v[190:193], v5, s[42:43] offset:16
	global_load_dwordx4 v[12:15], v5, s[22:23]
	global_load_dwordx4 v[248:251], v5, s[22:23] offset:16
	s_waitcnt vmcnt(14)
	s_cmp_lg_u32 s14, 0
	s_cbranch_scc1 .Lcb_hp_a
	v_mov_b32_e32 v120, 0
	v_mov_b32_e32 v121, 0
	v_mov_b32_e32 v122, 0
	v_mov_b32_e32 v123, 0
	v_mov_b32_e32 v124, 0
	v_mov_b32_e32 v125, 0
	v_mov_b32_e32 v126, 0
	v_mov_b32_e32 v127, 0
.Lcb_hp_a:
	s_cmp_lg_u32 s15, 0
	s_cbranch_scc1 .Lcb_hn_a
	v_mov_b32_e32 v128, 0
	v_mov_b32_e32 v129, 0
	v_mov_b32_e32 v130, 0
	v_mov_b32_e32 v131, 0
	v_mov_b32_e32 v132, 0
	v_mov_b32_e32 v133, 0
	v_mov_b32_e32 v134, 0
	v_mov_b32_e32 v135, 0
.Lcb_hn_a:
	v_lshlrev_b32_e32 v221, 16, v80
	v_lshlrev_b32_e32 v222, 16, v88
	v_and_b32_e32 v223, 0xffff0000, v80
	v_and_b32_e32 v224, 0xffff0000, v88
	v_add_f32_e32 v205, v222, v221
	v_add_f32_e32 v206, v224, v223
	v_lshlrev_b32_e32 v221, 16, v81
	v_lshlrev_b32_e32 v222, 16, v89
	v_and_b32_e32 v223, 0xffff0000, v81
	v_and_b32_e32 v224, 0xffff0000, v89
	v_add_f32_e32 v207, v222, v221
	v_add_f32_e32 v208, v224, v223
	v_lshlrev_b32_e32 v221, 16, v82
	v_lshlrev_b32_e32 v222, 16, v90
	v_and_b32_e32 v223, 0xffff0000, v82
	v_and_b32_e32 v224, 0xffff0000, v90
	v_add_f32_e32 v209, v222, v221
	v_add_f32_e32 v210, v224, v223
	v_lshlrev_b32_e32 v221, 16, v83
	v_lshlrev_b32_e32 v222, 16, v91
	v_and_b32_e32 v223, 0xffff0000, v83
	v_and_b32_e32 v224, 0xffff0000, v91
	v_add_f32_e32 v211, v222, v221
	v_add_f32_e32 v212, v224, v223
	v_lshlrev_b32_e32 v221, 16, v84
	v_lshlrev_b32_e32 v222, 16, v92
	v_and_b32_e32 v223, 0xffff0000, v84
	v_and_b32_e32 v224, 0xffff0000, v92
	v_add_f32_e32 v213, v222, v221
	v_add_f32_e32 v214, v224, v223
	v_lshlrev_b32_e32 v221, 16, v85
	v_lshlrev_b32_e32 v222, 16, v93
	v_and_b32_e32 v223, 0xffff0000, v85
	v_and_b32_e32 v224, 0xffff0000, v93
	v_add_f32_e32 v215, v222, v221
	v_add_f32_e32 v216, v224, v223
	v_lshlrev_b32_e32 v221, 16, v86
	v_lshlrev_b32_e32 v222, 16, v94
	v_and_b32_e32 v223, 0xffff0000, v86
	v_and_b32_e32 v224, 0xffff0000, v94
	v_add_f32_e32 v217, v222, v221
	v_add_f32_e32 v218, v224, v223
	v_lshlrev_b32_e32 v221, 16, v87
	v_lshlrev_b32_e32 v222, 16, v95
	v_and_b32_e32 v223, 0xffff0000, v87
	v_and_b32_e32 v224, 0xffff0000, v95
	v_add_f32_e32 v219, v222, v221
	v_add_f32_e32 v220, v224, v223
	v_mul_f32_e32 v229, v205, v205
	v_fmac_f32_e32 v229, v206, v206
	v_fmac_f32_e32 v229, v207, v207
	v_fmac_f32_e32 v229, v208, v208
	v_fmac_f32_e32 v229, v209, v209
	v_fmac_f32_e32 v229, v210, v210
	v_fmac_f32_e32 v229, v211, v211
	v_fmac_f32_e32 v229, v212, v212
	v_fmac_f32_e32 v229, v213, v213
	v_fmac_f32_e32 v229, v214, v214
	v_fmac_f32_e32 v229, v215, v215
	v_fmac_f32_e32 v229, v216, v216
	v_fmac_f32_e32 v229, v217, v217
	v_fmac_f32_e32 v229, v218, v218
	v_fmac_f32_e32 v229, v219, v219
	v_fmac_f32_e32 v229, v220, v220
	ds_bpermute_b32 v231, v9, v229
	s_waitcnt lgkmcnt(0)
	v_add_f32_e32 v229, v229, v231
	ds_bpermute_b32 v231, v10, v229
	s_waitcnt lgkmcnt(0)
	v_add_f32_e32 v229, v229, v231
	ds_bpermute_b32 v231, v11, v229
	s_waitcnt lgkmcnt(0)
	v_add_f32_e32 v229, v229, v231
	v_fmamk_f32 v229, v229, 0x3c000000, v195
	v_cmp_gt_f32_e32 vcc, s74, v229
	v_mul_f32_e32 v231, 0x4b800000, v229
	s_nop 1
	v_cndmask_b32_e32 v229, v229, v231, vcc
	v_rsq_f32_e32 v230, v229
	s_nop 0
	v_mul_f32_e32 v231, 0x45800000, v230
	v_cndmask_b32_e32 v230, v230, v231, vcc
	v_lshlrev_b32_e32 v221, 16, v96
	v_and_b32_e32 v222, 0xffff0000, v96
	v_mul_f32_e32 v205, v205, v230
	v_mul_f32_e32 v205, v16, v205
	v_mul_f32_e32 v205, v205, v221
	v_mul_f32_e32 v206, v206, v230
	v_mul_f32_e32 v206, v17, v206
	v_mul_f32_e32 v206, v206, v222
	v_cvt_pk_bf16_f32 v232, v205, v206
	v_lshlrev_b32_e32 v221, 16, v97
	v_and_b32_e32 v222, 0xffff0000, v97
	v_mul_f32_e32 v207, v207, v230
	v_mul_f32_e32 v207, v18, v207
	v_mul_f32_e32 v207, v207, v221
	v_mul_f32_e32 v208, v208, v230
	v_mul_f32_e32 v208, v19, v208
	v_mul_f32_e32 v208, v208, v222
	v_cvt_pk_bf16_f32 v233, v207, v208
	v_lshlrev_b32_e32 v221, 16, v98
	v_and_b32_e32 v222, 0xffff0000, v98
	v_mul_f32_e32 v209, v209, v230
	v_mul_f32_e32 v209, v20, v209
	v_mul_f32_e32 v209, v209, v221
	v_mul_f32_e32 v210, v210, v230
	v_mul_f32_e32 v210, v21, v210
	v_mul_f32_e32 v210, v210, v222
	v_cvt_pk_bf16_f32 v234, v209, v210
	v_lshlrev_b32_e32 v221, 16, v99
	v_and_b32_e32 v222, 0xffff0000, v99
	v_mul_f32_e32 v211, v211, v230
	v_mul_f32_e32 v211, v22, v211
	v_mul_f32_e32 v211, v211, v221
	v_mul_f32_e32 v212, v212, v230
	v_mul_f32_e32 v212, v23, v212
	v_mul_f32_e32 v212, v212, v222
	v_cvt_pk_bf16_f32 v235, v211, v212
	v_lshlrev_b32_e32 v221, 16, v100
	v_and_b32_e32 v222, 0xffff0000, v100
	v_mul_f32_e32 v213, v213, v230
	v_mul_f32_e32 v213, v24, v213
	v_mul_f32_e32 v213, v213, v221
	v_mul_f32_e32 v214, v214, v230
	v_mul_f32_e32 v214, v25, v214
	v_mul_f32_e32 v214, v214, v222
	v_cvt_pk_bf16_f32 v236, v213, v214
	v_lshlrev_b32_e32 v221, 16, v101
	v_and_b32_e32 v222, 0xffff0000, v101
	v_mul_f32_e32 v215, v215, v230
	v_mul_f32_e32 v215, v26, v215
	v_mul_f32_e32 v215, v215, v221
	v_mul_f32_e32 v216, v216, v230
	v_mul_f32_e32 v216, v27, v216
	v_mul_f32_e32 v216, v216, v222
	v_cvt_pk_bf16_f32 v237, v215, v216
	v_lshlrev_b32_e32 v221, 16, v102
	v_and_b32_e32 v222, 0xffff0000, v102
	v_mul_f32_e32 v217, v217, v230
	v_mul_f32_e32 v217, v28, v217
	v_mul_f32_e32 v217, v217, v221
	v_mul_f32_e32 v218, v218, v230
	v_mul_f32_e32 v218, v29, v218
	v_mul_f32_e32 v218, v218, v222
	v_cvt_pk_bf16_f32 v238, v217, v218
	v_lshlrev_b32_e32 v221, 16, v103
	v_and_b32_e32 v222, 0xffff0000, v103
	v_mul_f32_e32 v219, v219, v230
	v_mul_f32_e32 v219, v30, v219
	v_mul_f32_e32 v219, v219, v221
	v_mul_f32_e32 v220, v220, v230
	v_mul_f32_e32 v220, v31, v220
	v_mul_f32_e32 v220, v220, v222
	v_cvt_pk_bf16_f32 v239, v219, v220
	global_store_dwordx4 v0, v[232:235], s[24:25]
	global_store_dwordx4 v0, v[236:239], s[24:25] offset:16
	v_lshlrev_b32_e32 v221, 16, v120
	v_and_b32_e32 v222, 0xffff0000, v120
	v_lshlrev_b32_e32 v223, 16, v112
	v_and_b32_e32 v224, 0xffff0000, v112
	v_lshlrev_b32_e32 v225, 16, v128
	v_and_b32_e32 v226, 0xffff0000, v128
	v_lshlrev_b32_e32 v227, 16, v104
	v_and_b32_e32 v228, 0xffff0000, v104
	v_mul_f32_e32 v221, v32, v221
	v_fma_f32 v221, v48, v223, v221
	v_mul_f32_e32 v225, v64, v225
	v_add_f32_e32 v221, v221, v225
	v_mul_f32_e32 v221, v221, v227
	v_mul_f32_e32 v222, v33, v222
	v_fma_f32 v222, v49, v224, v222
	v_mul_f32_e32 v226, v65, v226
	v_add_f32_e32 v222, v222, v226
	v_mul_f32_e32 v222, v222, v228
	v_cvt_pk_bf16_f32 v240, v221, v222
	v_lshlrev_b32_e32 v221, 16, v121
	v_and_b32_e32 v222, 0xffff0000, v121
	v_lshlrev_b32_e32 v223, 16, v113
	v_and_b32_e32 v224, 0xffff0000, v113
	v_lshlrev_b32_e32 v225, 16, v129
	v_and_b32_e32 v226, 0xffff0000, v129
	v_lshlrev_b32_e32 v227, 16, v105
	v_and_b32_e32 v228, 0xffff0000, v105
	v_mul_f32_e32 v221, v34, v221
	v_fma_f32 v221, v50, v223, v221
	v_mul_f32_e32 v225, v66, v225
	v_add_f32_e32 v221, v221, v225
	v_mul_f32_e32 v221, v221, v227
	v_mul_f32_e32 v222, v35, v222
	v_fma_f32 v222, v51, v224, v222
	v_mul_f32_e32 v226, v67, v226
	v_add_f32_e32 v222, v222, v226
	v_mul_f32_e32 v222, v222, v228
	v_cvt_pk_bf16_f32 v241, v221, v222
	v_lshlrev_b32_e32 v221, 16, v122
	v_and_b32_e32 v222, 0xffff0000, v122
	v_lshlrev_b32_e32 v223, 16, v114
	v_and_b32_e32 v224, 0xffff0000, v114
	v_lshlrev_b32_e32 v225, 16, v130
	v_and_b32_e32 v226, 0xffff0000, v130
	v_lshlrev_b32_e32 v227, 16, v106
	v_and_b32_e32 v228, 0xffff0000, v106
	v_mul_f32_e32 v221, v36, v221
	v_fma_f32 v221, v52, v223, v221
	v_mul_f32_e32 v225, v68, v225
	v_add_f32_e32 v221, v221, v225
	v_mul_f32_e32 v221, v221, v227
	v_mul_f32_e32 v222, v37, v222
	v_fma_f32 v222, v53, v224, v222
	v_mul_f32_e32 v226, v69, v226
	v_add_f32_e32 v222, v222, v226
	v_mul_f32_e32 v222, v222, v228
	v_cvt_pk_bf16_f32 v242, v221, v222
	v_lshlrev_b32_e32 v221, 16, v123
	v_and_b32_e32 v222, 0xffff0000, v123
	v_lshlrev_b32_e32 v223, 16, v115
	v_and_b32_e32 v224, 0xffff0000, v115
	v_lshlrev_b32_e32 v225, 16, v131
	v_and_b32_e32 v226, 0xffff0000, v131
	v_lshlrev_b32_e32 v227, 16, v107
	v_and_b32_e32 v228, 0xffff0000, v107
	v_mul_f32_e32 v221, v38, v221
	v_fma_f32 v221, v54, v223, v221
	v_mul_f32_e32 v225, v70, v225
	v_add_f32_e32 v221, v221, v225
	v_mul_f32_e32 v221, v221, v227
	v_mul_f32_e32 v222, v39, v222
	v_fma_f32 v222, v55, v224, v222
	v_mul_f32_e32 v226, v71, v226
	v_add_f32_e32 v222, v222, v226
	v_mul_f32_e32 v222, v222, v228
	v_cvt_pk_bf16_f32 v243, v221, v222
	v_lshlrev_b32_e32 v221, 16, v124
	v_and_b32_e32 v222, 0xffff0000, v124
	v_lshlrev_b32_e32 v223, 16, v116
	v_and_b32_e32 v224, 0xffff0000, v116
	v_lshlrev_b32_e32 v225, 16, v132
	v_and_b32_e32 v226, 0xffff0000, v132
	v_lshlrev_b32_e32 v227, 16, v108
	v_and_b32_e32 v228, 0xffff0000, v108
	v_mul_f32_e32 v221, v40, v221
	v_fma_f32 v221, v56, v223, v221
	v_mul_f32_e32 v225, v72, v225
	v_add_f32_e32 v221, v221, v225
	v_mul_f32_e32 v221, v221, v227
	v_mul_f32_e32 v222, v41, v222
	v_fma_f32 v222, v57, v224, v222
	v_mul_f32_e32 v226, v73, v226
	v_add_f32_e32 v222, v222, v226
	v_mul_f32_e32 v222, v222, v228
	v_cvt_pk_bf16_f32 v244, v221, v222
	v_lshlrev_b32_e32 v221, 16, v125
	v_and_b32_e32 v222, 0xffff0000, v125
	v_lshlrev_b32_e32 v223, 16, v117
	v_and_b32_e32 v224, 0xffff0000, v117
	v_lshlrev_b32_e32 v225, 16, v133
	v_and_b32_e32 v226, 0xffff0000, v133
	v_lshlrev_b32_e32 v227, 16, v109
	v_and_b32_e32 v228, 0xffff0000, v109
	v_mul_f32_e32 v221, v42, v221
	v_fma_f32 v221, v58, v223, v221
	v_mul_f32_e32 v225, v74, v225
	v_add_f32_e32 v221, v221, v225
	v_mul_f32_e32 v221, v221, v227
	v_mul_f32_e32 v222, v43, v222
	v_fma_f32 v222, v59, v224, v222
	v_mul_f32_e32 v226, v75, v226
	v_add_f32_e32 v222, v222, v226
	v_mul_f32_e32 v222, v222, v228
	v_cvt_pk_bf16_f32 v245, v221, v222
	v_lshlrev_b32_e32 v221, 16, v126
	v_and_b32_e32 v222, 0xffff0000, v126
	v_lshlrev_b32_e32 v223, 16, v118
	v_and_b32_e32 v224, 0xffff0000, v118
	v_lshlrev_b32_e32 v225, 16, v134
	v_and_b32_e32 v226, 0xffff0000, v134
	v_lshlrev_b32_e32 v227, 16, v110
	v_and_b32_e32 v228, 0xffff0000, v110
	v_mul_f32_e32 v221, v44, v221
	v_fma_f32 v221, v60, v223, v221
	v_mul_f32_e32 v225, v76, v225
	v_add_f32_e32 v221, v221, v225
	v_mul_f32_e32 v221, v221, v227
	v_mul_f32_e32 v222, v45, v222
	v_fma_f32 v222, v61, v224, v222
	v_mul_f32_e32 v226, v77, v226
	v_add_f32_e32 v222, v222, v226
	v_mul_f32_e32 v222, v222, v228
	v_cvt_pk_bf16_f32 v246, v221, v222
	v_lshlrev_b32_e32 v221, 16, v127
	v_and_b32_e32 v222, 0xffff0000, v127
	v_lshlrev_b32_e32 v223, 16, v119
	v_and_b32_e32 v224, 0xffff0000, v119
	v_lshlrev_b32_e32 v225, 16, v135
	v_and_b32_e32 v226, 0xffff0000, v135
	v_lshlrev_b32_e32 v227, 16, v111
	v_and_b32_e32 v228, 0xffff0000, v111
	v_mul_f32_e32 v221, v46, v221
	v_fma_f32 v221, v62, v223, v221
	v_mul_f32_e32 v225, v78, v225
	v_add_f32_e32 v221, v221, v225
	v_mul_f32_e32 v221, v221, v227
	v_mul_f32_e32 v222, v47, v222
	v_fma_f32 v222, v63, v224, v222
	v_mul_f32_e32 v226, v79, v226
	v_add_f32_e32 v222, v222, v226
	v_mul_f32_e32 v222, v222, v228
	v_cvt_pk_bf16_f32 v247, v221, v222
	global_store_dwordx4 v0, v[240:243], s[24:25] offset:2048
	global_store_dwordx4 v0, v[244:247], s[24:25] offset:2064
	s_add_u32 s24, s24, s26
	s_addc_u32 s25, s25, s27
	s_add_i32 s16, s16, s6
	s_cmpk_lt_i32 s16, 0x3000
	s_cbranch_scc0 .Lcb_last_b
	s_add_u32 s38, s38, s28
	s_addc_u32 s39, s39, s29
	s_add_u32 s40, s40, s28
	s_addc_u32 s41, s41, s29
	s_add_u32 s34, s34, s36
	s_addc_u32 s35, s35, s37
	s_cmpk_lt_i32 s16, 0x1000
	s_cselect_b32 s22, 0xff, s20
	s_cselect_b32 s23, 1, s21
	s_and_b32 s30, s16, s22
	s_lshl_b32 s17, s23, 14
	s_cmp_ge_u32 s30, s23
	s_cselect_b32 s42, s17, 0
	s_cselect_b32 s14, 1, 0
	s_add_i32 s30, s30, s23
	s_cmp_le_u32 s30, s22
	s_cselect_b32 s30, s17, 0
	s_cselect_b32 s15, 1, 0
	s_sub_u32 s42, s34, s42
	s_subb_u32 s43, s35, 0
	s_add_u32 s22, s34, s30
	s_addc_u32 s23, s35, 0
	global_load_dwordx4 v[80:83], v0, s[38:39]
	global_load_dwordx4 v[84:87], v0, s[38:39] offset:16
	global_load_dwordx4 v[88:91], v0, s[40:41]
	global_load_dwordx4 v[92:95], v0, s[40:41] offset:16
	global_load_dwordx4 v[96:99], v3, s[34:35]
	global_load_dwordx4 v[100:103], v3, s[34:35] offset:16
	global_load_dwordx4 v[104:107], v4, s[34:35]
	global_load_dwordx4 v[108:111], v4, s[34:35] offset:16
	global_load_dwordx4 v[112:115], v5, s[34:35]
	global_load_dwordx4 v[116:119], v5, s[34:35] offset:16
	global_load_dwordx4 v[120:123], v5, s[42:43]
	global_load_dwordx4 v[124:127], v5, s[42:43] offset:16
	global_load_dwordx4 v[128:131], v5, s[22:23]
	global_load_dwordx4 v[132:135], v5, s[22:23] offset:16
	s_waitcnt vmcnt(14)
	s_cmp_lg_u32 s4, 0
	s_cbranch_scc1 .Lcb_hp_b
	v_mov_b32_e32 v186, 0
	v_mov_b32_e32 v187, 0
	v_mov_b32_e32 v188, 0
	v_mov_b32_e32 v189, 0
	v_mov_b32_e32 v190, 0
	v_mov_b32_e32 v191, 0
	v_mov_b32_e32 v192, 0
	v_mov_b32_e32 v193, 0
.Lcb_hp_b:
	s_cmp_lg_u32 s5, 0
	s_cbranch_scc1 .Lcb_hn_b
	v_mov_b32_e32 v12, 0
	v_mov_b32_e32 v13, 0
	v_mov_b32_e32 v14, 0
	v_mov_b32_e32 v15, 0
	v_mov_b32_e32 v248, 0
	v_mov_b32_e32 v249, 0
	v_mov_b32_e32 v250, 0
	v_mov_b32_e32 v251, 0
.Lcb_hn_b:
	v_lshlrev_b32_e32 v221, 16, v136
	v_lshlrev_b32_e32 v222, 16, v144
	v_and_b32_e32 v223, 0xffff0000, v136
	v_and_b32_e32 v224, 0xffff0000, v144
	v_add_f32_e32 v205, v222, v221
	v_add_f32_e32 v206, v224, v223
	v_lshlrev_b32_e32 v221, 16, v137
	v_lshlrev_b32_e32 v222, 16, v145
	v_and_b32_e32 v223, 0xffff0000, v137
	v_and_b32_e32 v224, 0xffff0000, v145
	v_add_f32_e32 v207, v222, v221
	v_add_f32_e32 v208, v224, v223
	v_lshlrev_b32_e32 v221, 16, v138
	v_lshlrev_b32_e32 v222, 16, v146
	v_and_b32_e32 v223, 0xffff0000, v138
	v_and_b32_e32 v224, 0xffff0000, v146
	v_add_f32_e32 v209, v222, v221
	v_add_f32_e32 v210, v224, v223
	v_lshlrev_b32_e32 v221, 16, v139
	v_lshlrev_b32_e32 v222, 16, v147
	v_and_b32_e32 v223, 0xffff0000, v139
	v_and_b32_e32 v224, 0xffff0000, v147
	v_add_f32_e32 v211, v222, v221
	v_add_f32_e32 v212, v224, v223
	v_lshlrev_b32_e32 v221, 16, v140
	v_lshlrev_b32_e32 v222, 16, v148
	v_and_b32_e32 v223, 0xffff0000, v140
	v_and_b32_e32 v224, 0xffff0000, v148
	v_add_f32_e32 v213, v222, v221
	v_add_f32_e32 v214, v224, v223
	v_lshlrev_b32_e32 v221, 16, v141
	v_lshlrev_b32_e32 v222, 16, v149
	v_and_b32_e32 v223, 0xffff0000, v141
	v_and_b32_e32 v224, 0xffff0000, v149
	v_add_f32_e32 v215, v222, v221
	v_add_f32_e32 v216, v224, v223
	v_lshlrev_b32_e32 v221, 16, v142
	v_lshlrev_b32_e32 v222, 16, v150
	v_and_b32_e32 v223, 0xffff0000, v142
	v_and_b32_e32 v224, 0xffff0000, v150
	v_add_f32_e32 v217, v222, v221
	v_add_f32_e32 v218, v224, v223
	v_lshlrev_b32_e32 v221, 16, v143
	v_lshlrev_b32_e32 v222, 16, v151
	v_and_b32_e32 v223, 0xffff0000, v143
	v_and_b32_e32 v224, 0xffff0000, v151
	v_add_f32_e32 v219, v222, v221
	v_add_f32_e32 v220, v224, v223
	v_mul_f32_e32 v229, v205, v205
	v_fmac_f32_e32 v229, v206, v206
	v_fmac_f32_e32 v229, v207, v207
	v_fmac_f32_e32 v229, v208, v208
	v_fmac_f32_e32 v229, v209, v209
	v_fmac_f32_e32 v229, v210, v210
	v_fmac_f32_e32 v229, v211, v211
	v_fmac_f32_e32 v229, v212, v212
	v_fmac_f32_e32 v229, v213, v213
	v_fmac_f32_e32 v229, v214, v214
	v_fmac_f32_e32 v229, v215, v215
	v_fmac_f32_e32 v229, v216, v216
	v_fmac_f32_e32 v229, v217, v217
	v_fmac_f32_e32 v229, v218, v218
	v_fmac_f32_e32 v229, v219, v219
	v_fmac_f32_e32 v229, v220, v220
	ds_bpermute_b32 v231, v9, v229
	s_waitcnt lgkmcnt(0)
	v_add_f32_e32 v229, v229, v231
	ds_bpermute_b32 v231, v10, v229
	s_waitcnt lgkmcnt(0)
	v_add_f32_e32 v229, v229, v231
	ds_bpermute_b32 v231, v11, v229
	s_waitcnt lgkmcnt(0)
	v_add_f32_e32 v229, v229, v231
	v_fmamk_f32 v229, v229, 0x3c000000, v195
	v_cmp_gt_f32_e32 vcc, s74, v229
	v_mul_f32_e32 v231, 0x4b800000, v229
	s_nop 1
	v_cndmask_b32_e32 v229, v229, v231, vcc
	v_rsq_f32_e32 v230, v229
	s_nop 0
	v_mul_f32_e32 v231, 0x45800000, v230
	v_cndmask_b32_e32 v230, v230, v231, vcc
	v_lshlrev_b32_e32 v221, 16, v162
	v_and_b32_e32 v222, 0xffff0000, v162
	v_mul_f32_e32 v205, v205, v230
	v_mul_f32_e32 v205, v16, v205
	v_mul_f32_e32 v205, v205, v221
	v_mul_f32_e32 v206, v206, v230
	v_mul_f32_e32 v206, v17, v206
	v_mul_f32_e32 v206, v206, v222
	v_cvt_pk_bf16_f32 v232, v205, v206
	v_lshlrev_b32_e32 v221, 16, v163
	v_and_b32_e32 v222, 0xffff0000, v163
	v_mul_f32_e32 v207, v207, v230
	v_mul_f32_e32 v207, v18, v207
	v_mul_f32_e32 v207, v207, v221
	v_mul_f32_e32 v208, v208, v230
	v_mul_f32_e32 v208, v19, v208
	v_mul_f32_e32 v208, v208, v222
	v_cvt_pk_bf16_f32 v233, v207, v208
	v_lshlrev_b32_e32 v221, 16, v164
	v_and_b32_e32 v222, 0xffff0000, v164
	v_mul_f32_e32 v209, v209, v230
	v_mul_f32_e32 v209, v20, v209
	v_mul_f32_e32 v209, v209, v221
	v_mul_f32_e32 v210, v210, v230
	v_mul_f32_e32 v210, v21, v210
	v_mul_f32_e32 v210, v210, v222
	v_cvt_pk_bf16_f32 v234, v209, v210
	v_lshlrev_b32_e32 v221, 16, v165
	v_and_b32_e32 v222, 0xffff0000, v165
	v_mul_f32_e32 v211, v211, v230
	v_mul_f32_e32 v211, v22, v211
	v_mul_f32_e32 v211, v211, v221
	v_mul_f32_e32 v212, v212, v230
	v_mul_f32_e32 v212, v23, v212
	v_mul_f32_e32 v212, v212, v222
	v_cvt_pk_bf16_f32 v235, v211, v212
	v_lshlrev_b32_e32 v221, 16, v166
	v_and_b32_e32 v222, 0xffff0000, v166
	v_mul_f32_e32 v213, v213, v230
	v_mul_f32_e32 v213, v24, v213
	v_mul_f32_e32 v213, v213, v221
	v_mul_f32_e32 v214, v214, v230
	v_mul_f32_e32 v214, v25, v214
	v_mul_f32_e32 v214, v214, v222
	v_cvt_pk_bf16_f32 v236, v213, v214
	v_lshlrev_b32_e32 v221, 16, v167
	v_and_b32_e32 v222, 0xffff0000, v167
	v_mul_f32_e32 v215, v215, v230
	v_mul_f32_e32 v215, v26, v215
	v_mul_f32_e32 v215, v215, v221
	v_mul_f32_e32 v216, v216, v230
	v_mul_f32_e32 v216, v27, v216
	v_mul_f32_e32 v216, v216, v222
	v_cvt_pk_bf16_f32 v237, v215, v216
	v_lshlrev_b32_e32 v221, 16, v168
	v_and_b32_e32 v222, 0xffff0000, v168
	v_mul_f32_e32 v217, v217, v230
	v_mul_f32_e32 v217, v28, v217
	v_mul_f32_e32 v217, v217, v221
	v_mul_f32_e32 v218, v218, v230
	v_mul_f32_e32 v218, v29, v218
	v_mul_f32_e32 v218, v218, v222
	v_cvt_pk_bf16_f32 v238, v217, v218
	v_lshlrev_b32_e32 v221, 16, v169
	v_and_b32_e32 v222, 0xffff0000, v169
	v_mul_f32_e32 v219, v219, v230
	v_mul_f32_e32 v219, v30, v219
	v_mul_f32_e32 v219, v219, v221
	v_mul_f32_e32 v220, v220, v230
	v_mul_f32_e32 v220, v31, v220
	v_mul_f32_e32 v220, v220, v222
	v_cvt_pk_bf16_f32 v239, v219, v220
	global_store_dwordx4 v0, v[232:235], s[24:25]
	global_store_dwordx4 v0, v[236:239], s[24:25] offset:16
	v_lshlrev_b32_e32 v221, 16, v186
	v_and_b32_e32 v222, 0xffff0000, v186
	v_lshlrev_b32_e32 v223, 16, v178
	v_and_b32_e32 v224, 0xffff0000, v178
	v_lshlrev_b32_e32 v225, 16, v12
	v_and_b32_e32 v226, 0xffff0000, v12
	v_lshlrev_b32_e32 v227, 16, v170
	v_and_b32_e32 v228, 0xffff0000, v170
	v_mul_f32_e32 v221, v32, v221
	v_fma_f32 v221, v48, v223, v221
	v_mul_f32_e32 v225, v64, v225
	v_add_f32_e32 v221, v221, v225
	v_mul_f32_e32 v221, v221, v227
	v_mul_f32_e32 v222, v33, v222
	v_fma_f32 v222, v49, v224, v222
	v_mul_f32_e32 v226, v65, v226
	v_add_f32_e32 v222, v222, v226
	v_mul_f32_e32 v222, v222, v228
	v_cvt_pk_bf16_f32 v240, v221, v222
	v_lshlrev_b32_e32 v221, 16, v187
	v_and_b32_e32 v222, 0xffff0000, v187
	v_lshlrev_b32_e32 v223, 16, v179
	v_and_b32_e32 v224, 0xffff0000, v179
	v_lshlrev_b32_e32 v225, 16, v13
	v_and_b32_e32 v226, 0xffff0000, v13
	v_lshlrev_b32_e32 v227, 16, v171
	v_and_b32_e32 v228, 0xffff0000, v171
	v_mul_f32_e32 v221, v34, v221
	v_fma_f32 v221, v50, v223, v221
	v_mul_f32_e32 v225, v66, v225
	v_add_f32_e32 v221, v221, v225
	v_mul_f32_e32 v221, v221, v227
	v_mul_f32_e32 v222, v35, v222
	v_fma_f32 v222, v51, v224, v222
	v_mul_f32_e32 v226, v67, v226
	v_add_f32_e32 v222, v222, v226
	v_mul_f32_e32 v222, v222, v228
	v_cvt_pk_bf16_f32 v241, v221, v222
	v_lshlrev_b32_e32 v221, 16, v188
	v_and_b32_e32 v222, 0xffff0000, v188
	v_lshlrev_b32_e32 v223, 16, v180
	v_and_b32_e32 v224, 0xffff0000, v180
	v_lshlrev_b32_e32 v225, 16, v14
	v_and_b32_e32 v226, 0xffff0000, v14
	v_lshlrev_b32_e32 v227, 16, v172
	v_and_b32_e32 v228, 0xffff0000, v172
	v_mul_f32_e32 v221, v36, v221
	v_fma_f32 v221, v52, v223, v221
	v_mul_f32_e32 v225, v68, v225
	v_add_f32_e32 v221, v221, v225
	v_mul_f32_e32 v221, v221, v227
	v_mul_f32_e32 v222, v37, v222
	v_fma_f32 v222, v53, v224, v222
	v_mul_f32_e32 v226, v69, v226
	v_add_f32_e32 v222, v222, v226
	v_mul_f32_e32 v222, v222, v228
	v_cvt_pk_bf16_f32 v242, v221, v222
	v_lshlrev_b32_e32 v221, 16, v189
	v_and_b32_e32 v222, 0xffff0000, v189
	v_lshlrev_b32_e32 v223, 16, v181
	v_and_b32_e32 v224, 0xffff0000, v181
	v_lshlrev_b32_e32 v225, 16, v15
	v_and_b32_e32 v226, 0xffff0000, v15
	v_lshlrev_b32_e32 v227, 16, v173
	v_and_b32_e32 v228, 0xffff0000, v173
	v_mul_f32_e32 v221, v38, v221
	v_fma_f32 v221, v54, v223, v221
	v_mul_f32_e32 v225, v70, v225
	v_add_f32_e32 v221, v221, v225
	v_mul_f32_e32 v221, v221, v227
	v_mul_f32_e32 v222, v39, v222
	v_fma_f32 v222, v55, v224, v222
	v_mul_f32_e32 v226, v71, v226
	v_add_f32_e32 v222, v222, v226
	v_mul_f32_e32 v222, v222, v228
	v_cvt_pk_bf16_f32 v243, v221, v222
	v_lshlrev_b32_e32 v221, 16, v190
	v_and_b32_e32 v222, 0xffff0000, v190
	v_lshlrev_b32_e32 v223, 16, v182
	v_and_b32_e32 v224, 0xffff0000, v182
	v_lshlrev_b32_e32 v225, 16, v248
	v_and_b32_e32 v226, 0xffff0000, v248
	v_lshlrev_b32_e32 v227, 16, v174
	v_and_b32_e32 v228, 0xffff0000, v174
	v_mul_f32_e32 v221, v40, v221
	v_fma_f32 v221, v56, v223, v221
	v_mul_f32_e32 v225, v72, v225
	v_add_f32_e32 v221, v221, v225
	v_mul_f32_e32 v221, v221, v227
	v_mul_f32_e32 v222, v41, v222
	v_fma_f32 v222, v57, v224, v222
	v_mul_f32_e32 v226, v73, v226
	v_add_f32_e32 v222, v222, v226
	v_mul_f32_e32 v222, v222, v228
	v_cvt_pk_bf16_f32 v244, v221, v222
	v_lshlrev_b32_e32 v221, 16, v191
	v_and_b32_e32 v222, 0xffff0000, v191
	v_lshlrev_b32_e32 v223, 16, v183
	v_and_b32_e32 v224, 0xffff0000, v183
	v_lshlrev_b32_e32 v225, 16, v249
	v_and_b32_e32 v226, 0xffff0000, v249
	v_lshlrev_b32_e32 v227, 16, v175
	v_and_b32_e32 v228, 0xffff0000, v175
	v_mul_f32_e32 v221, v42, v221
	v_fma_f32 v221, v58, v223, v221
	v_mul_f32_e32 v225, v74, v225
	v_add_f32_e32 v221, v221, v225
	v_mul_f32_e32 v221, v221, v227
	v_mul_f32_e32 v222, v43, v222
	v_fma_f32 v222, v59, v224, v222
	v_mul_f32_e32 v226, v75, v226
	v_add_f32_e32 v222, v222, v226
	v_mul_f32_e32 v222, v222, v228
	v_cvt_pk_bf16_f32 v245, v221, v222
	v_lshlrev_b32_e32 v221, 16, v192
	v_and_b32_e32 v222, 0xffff0000, v192
	v_lshlrev_b32_e32 v223, 16, v184
	v_and_b32_e32 v224, 0xffff0000, v184
	v_lshlrev_b32_e32 v225, 16, v250
	v_and_b32_e32 v226, 0xffff0000, v250
	v_lshlrev_b32_e32 v227, 16, v176
	v_and_b32_e32 v228, 0xffff0000, v176
	v_mul_f32_e32 v221, v44, v221
	v_fma_f32 v221, v60, v223, v221
	v_mul_f32_e32 v225, v76, v225
	v_add_f32_e32 v221, v221, v225
	v_mul_f32_e32 v221, v221, v227
	v_mul_f32_e32 v222, v45, v222
	v_fma_f32 v222, v61, v224, v222
	v_mul_f32_e32 v226, v77, v226
	v_add_f32_e32 v222, v222, v226
	v_mul_f32_e32 v222, v222, v228
	v_cvt_pk_bf16_f32 v246, v221, v222
	v_lshlrev_b32_e32 v221, 16, v193
	v_and_b32_e32 v222, 0xffff0000, v193
	v_lshlrev_b32_e32 v223, 16, v185
	v_and_b32_e32 v224, 0xffff0000, v185
	v_lshlrev_b32_e32 v225, 16, v251
	v_and_b32_e32 v226, 0xffff0000, v251
	v_lshlrev_b32_e32 v227, 16, v177
	v_and_b32_e32 v228, 0xffff0000, v177
	v_mul_f32_e32 v221, v46, v221
	v_fma_f32 v221, v62, v223, v221
	v_mul_f32_e32 v225, v78, v225
	v_add_f32_e32 v221, v221, v225
	v_mul_f32_e32 v221, v221, v227
	v_mul_f32_e32 v222, v47, v222
	v_fma_f32 v222, v63, v224, v222
	v_mul_f32_e32 v226, v79, v226
	v_add_f32_e32 v222, v222, v226
	v_mul_f32_e32 v222, v222, v228
	v_cvt_pk_bf16_f32 v247, v221, v222
	global_store_dwordx4 v0, v[240:243], s[24:25] offset:2048
	global_store_dwordx4 v0, v[244:247], s[24:25] offset:2064
	s_add_u32 s24, s24, s26
	s_addc_u32 s25, s25, s27
	s_branch .Lcb_loop
.Lcb_last_a:
	s_waitcnt vmcnt(0)
	s_cmp_lg_u32 s14, 0
	s_cbranch_scc1 .Lcb_hp_al
	v_mov_b32_e32 v120, 0
	v_mov_b32_e32 v121, 0
	v_mov_b32_e32 v122, 0
	v_mov_b32_e32 v123, 0
	v_mov_b32_e32 v124, 0
	v_mov_b32_e32 v125, 0
	v_mov_b32_e32 v126, 0
	v_mov_b32_e32 v127, 0

.Lcb_hn_al:
	v_lshlrev_b32_e32 v221, 16, v80
	v_lshlrev_b32_e32 v222, 16, v88
	v_and_b32_e32 v223, 0xffff0000, v80
	v_and_b32_e32 v224, 0xffff0000, v88
	v_add_f32_e32 v205, v222, v221
	v_add_f32_e32 v206, v224, v223
	v_lshlrev_b32_e32 v221, 16, v81
	v_lshlrev_b32_e32 v222, 16, v89
	v_and_b32_e32 v223, 0xffff0000, v81
	v_and_b32_e32 v224, 0xffff0000, v89
	v_add_f32_e32 v207, v222, v221
	v_add_f32_e32 v208, v224, v223
	v_lshlrev_b32_e32 v221, 16, v82
	v_lshlrev_b32_e32 v222, 16, v90
	v_and_b32_e32 v223, 0xffff0000, v82
	v_and_b32_e32 v224, 0xffff0000, v90
	v_add_f32_e32 v209, v222, v221
	v_add_f32_e32 v210, v224, v223
	v_lshlrev_b32_e32 v221, 16, v83
	v_lshlrev_b32_e32 v222, 16, v91
	v_and_b32_e32 v223, 0xffff0000, v83
	v_and_b32_e32 v224, 0xffff0000, v91
	v_add_f32_e32 v211, v222, v221
	v_add_f32_e32 v212, v224, v223
	v_lshlrev_b32_e32 v221, 16, v84
	v_lshlrev_b32_e32 v222, 16, v92
	v_and_b32_e32 v223, 0xffff0000, v84
	v_and_b32_e32 v224, 0xffff0000, v92
	v_add_f32_e32 v213, v222, v221
	v_add_f32_e32 v214, v224, v223
	v_lshlrev_b32_e32 v221, 16, v85
	v_lshlrev_b32_e32 v222, 16, v93
	v_and_b32_e32 v223, 0xffff0000, v85
	v_and_b32_e32 v224, 0xffff0000, v93
	v_add_f32_e32 v215, v222, v221
	v_add_f32_e32 v216, v224, v223
	v_lshlrev_b32_e32 v221, 16, v86
	v_lshlrev_b32_e32 v222, 16, v94
	v_and_b32_e32 v223, 0xffff0000, v86
	v_and_b32_e32 v224, 0xffff0000, v94
	v_add_f32_e32 v217, v222, v221
	v_add_f32_e32 v218, v224, v223
	v_lshlrev_b32_e32 v221, 16, v87
	v_lshlrev_b32_e32 v222, 16, v95
	v_and_b32_e32 v223, 0xffff0000, v87
	v_and_b32_e32 v224, 0xffff0000, v95
	v_add_f32_e32 v219, v222, v221
	v_add_f32_e32 v220, v224, v223
	v_mul_f32_e32 v229, v205, v205
	v_fmac_f32_e32 v229, v206, v206
	v_fmac_f32_e32 v229, v207, v207
	v_fmac_f32_e32 v229, v208, v208
	v_fmac_f32_e32 v229, v209, v209
	v_fmac_f32_e32 v229, v210, v210
	v_fmac_f32_e32 v229, v211, v211
	v_fmac_f32_e32 v229, v212, v212
	v_fmac_f32_e32 v229, v213, v213
	v_fmac_f32_e32 v229, v214, v214
	v_fmac_f32_e32 v229, v215, v215
	v_fmac_f32_e32 v229, v216, v216
	v_fmac_f32_e32 v229, v217, v217
	v_fmac_f32_e32 v229, v218, v218
	v_fmac_f32_e32 v229, v219, v219
	v_fmac_f32_e32 v229, v220, v220
	ds_bpermute_b32 v231, v9, v229
	s_waitcnt lgkmcnt(0)
	v_add_f32_e32 v229, v229, v231
	ds_bpermute_b32 v231, v10, v229
	s_waitcnt lgkmcnt(0)
	v_add_f32_e32 v229, v229, v231
	ds_bpermute_b32 v231, v11, v229
	s_waitcnt lgkmcnt(0)
	v_add_f32_e32 v229, v229, v231
	v_fmamk_f32 v229, v229, 0x3c000000, v195
	v_cmp_gt_f32_e32 vcc, s74, v229
	v_mul_f32_e32 v231, 0x4b800000, v229
	s_nop 1
	v_cndmask_b32_e32 v229, v229, v231, vcc
	v_rsq_f32_e32 v230, v229
	s_nop 0
	v_mul_f32_e32 v231, 0x45800000, v230
	v_cndmask_b32_e32 v230, v230, v231, vcc
	v_lshlrev_b32_e32 v221, 16, v96
	v_and_b32_e32 v222, 0xffff0000, v96
	v_mul_f32_e32 v205, v205, v230
	v_mul_f32_e32 v205, v16, v205
	v_mul_f32_e32 v205, v205, v221
	v_mul_f32_e32 v206, v206, v230
	v_mul_f32_e32 v206, v17, v206
	v_mul_f32_e32 v206, v206, v222
	v_cvt_pk_bf16_f32 v232, v205, v206
	v_lshlrev_b32_e32 v221, 16, v97
	v_and_b32_e32 v222, 0xffff0000, v97
	v_mul_f32_e32 v207, v207, v230
	v_mul_f32_e32 v207, v18, v207
	v_mul_f32_e32 v207, v207, v221
	v_mul_f32_e32 v208, v208, v230
	v_mul_f32_e32 v208, v19, v208
	v_mul_f32_e32 v208, v208, v222
	v_cvt_pk_bf16_f32 v233, v207, v208
	v_lshlrev_b32_e32 v221, 16, v98
	v_and_b32_e32 v222, 0xffff0000, v98
	v_mul_f32_e32 v209, v209, v230
	v_mul_f32_e32 v209, v20, v209
	v_mul_f32_e32 v209, v209, v221
	v_mul_f32_e32 v210, v210, v230
	v_mul_f32_e32 v210, v21, v210
	v_mul_f32_e32 v210, v210, v222
	v_cvt_pk_bf16_f32 v234, v209, v210
	v_lshlrev_b32_e32 v221, 16, v99
	v_and_b32_e32 v222, 0xffff0000, v99
	v_mul_f32_e32 v211, v211, v230
	v_mul_f32_e32 v211, v22, v211
	v_mul_f32_e32 v211, v211, v221
	v_mul_f32_e32 v212, v212, v230
	v_mul_f32_e32 v212, v23, v212
	v_mul_f32_e32 v212, v212, v222
	v_cvt_pk_bf16_f32 v235, v211, v212
	v_lshlrev_b32_e32 v221, 16, v100
	v_and_b32_e32 v222, 0xffff0000, v100
	v_mul_f32_e32 v213, v213, v230
	v_mul_f32_e32 v213, v24, v213
	v_mul_f32_e32 v213, v213, v221
	v_mul_f32_e32 v214, v214, v230
	v_mul_f32_e32 v214, v25, v214
	v_mul_f32_e32 v214, v214, v222
	v_cvt_pk_bf16_f32 v236, v213, v214
	v_lshlrev_b32_e32 v221, 16, v101
	v_and_b32_e32 v222, 0xffff0000, v101
	v_mul_f32_e32 v215, v215, v230
	v_mul_f32_e32 v215, v26, v215
	v_mul_f32_e32 v215, v215, v221
	v_mul_f32_e32 v216, v216, v230
	v_mul_f32_e32 v216, v27, v216
	v_mul_f32_e32 v216, v216, v222
	v_cvt_pk_bf16_f32 v237, v215, v216
	v_lshlrev_b32_e32 v221, 16, v102
	v_and_b32_e32 v222, 0xffff0000, v102
	v_mul_f32_e32 v217, v217, v230
	v_mul_f32_e32 v217, v28, v217
	v_mul_f32_e32 v217, v217, v221
	v_mul_f32_e32 v218, v218, v230
	v_mul_f32_e32 v218, v29, v218
	v_mul_f32_e32 v218, v218, v222
	v_cvt_pk_bf16_f32 v238, v217, v218
	v_lshlrev_b32_e32 v221, 16, v103
	v_and_b32_e32 v222, 0xffff0000, v103
	v_mul_f32_e32 v219, v219, v230
	v_mul_f32_e32 v219, v30, v219
	v_mul_f32_e32 v219, v219, v221
	v_mul_f32_e32 v220, v220, v230
	v_mul_f32_e32 v220, v31, v220
	v_mul_f32_e32 v220, v220, v222
	v_cvt_pk_bf16_f32 v239, v219, v220
	global_store_dwordx4 v0, v[232:235], s[24:25]
	global_store_dwordx4 v0, v[236:239], s[24:25] offset:16
	v_lshlrev_b32_e32 v221, 16, v120
	v_and_b32_e32 v222, 0xffff0000, v120
	v_lshlrev_b32_e32 v223, 16, v112
	v_and_b32_e32 v224, 0xffff0000, v112
	v_lshlrev_b32_e32 v225, 16, v128
	v_and_b32_e32 v226, 0xffff0000, v128
	v_lshlrev_b32_e32 v227, 16, v104
	v_and_b32_e32 v228, 0xffff0000, v104
	v_mul_f32_e32 v221, v32, v221
	v_fma_f32 v221, v48, v223, v221
	v_mul_f32_e32 v225, v64, v225
	v_add_f32_e32 v221, v221, v225
	v_mul_f32_e32 v221, v221, v227
	v_mul_f32_e32 v222, v33, v222
	v_fma_f32 v222, v49, v224, v222
	v_mul_f32_e32 v226, v65, v226
	v_add_f32_e32 v222, v222, v226
	v_mul_f32_e32 v222, v222, v228
	v_cvt_pk_bf16_f32 v240, v221, v222
	v_lshlrev_b32_e32 v221, 16, v121
	v_and_b32_e32 v222, 0xffff0000, v121
	v_lshlrev_b32_e32 v223, 16, v113
	v_and_b32_e32 v224, 0xffff0000, v113
	v_lshlrev_b32_e32 v225, 16, v129
	v_and_b32_e32 v226, 0xffff0000, v129
	v_lshlrev_b32_e32 v227, 16, v105
	v_and_b32_e32 v228, 0xffff0000, v105
	v_mul_f32_e32 v221, v34, v221
	v_fma_f32 v221, v50, v223, v221
	v_mul_f32_e32 v225, v66, v225
	v_add_f32_e32 v221, v221, v225
	v_mul_f32_e32 v221, v221, v227
	v_mul_f32_e32 v222, v35, v222
	v_fma_f32 v222, v51, v224, v222
	v_mul_f32_e32 v226, v67, v226
	v_add_f32_e32 v222, v222, v226
	v_mul_f32_e32 v222, v222, v228
	v_cvt_pk_bf16_f32 v241, v221, v222
	v_lshlrev_b32_e32 v221, 16, v122
	v_and_b32_e32 v222, 0xffff0000, v122
	v_lshlrev_b32_e32 v223, 16, v114
	v_and_b32_e32 v224, 0xffff0000, v114
	v_lshlrev_b32_e32 v225, 16, v130
	v_and_b32_e32 v226, 0xffff0000, v130
	v_lshlrev_b32_e32 v227, 16, v106
	v_and_b32_e32 v228, 0xffff0000, v106
	v_mul_f32_e32 v221, v36, v221
	v_fma_f32 v221, v52, v223, v221
	v_mul_f32_e32 v225, v68, v225
	v_add_f32_e32 v221, v221, v225
	v_mul_f32_e32 v221, v221, v227
	v_mul_f32_e32 v222, v37, v222
	v_fma_f32 v222, v53, v224, v222
	v_mul_f32_e32 v226, v69, v226
	v_add_f32_e32 v222, v222, v226
	v_mul_f32_e32 v222, v222, v228
	v_cvt_pk_bf16_f32 v242, v221, v222
	v_lshlrev_b32_e32 v221, 16, v123
	v_and_b32_e32 v222, 0xffff0000, v123
	v_lshlrev_b32_e32 v223, 16, v115
	v_and_b32_e32 v224, 0xffff0000, v115
	v_lshlrev_b32_e32 v225, 16, v131
	v_and_b32_e32 v226, 0xffff0000, v131
	v_lshlrev_b32_e32 v227, 16, v107
	v_and_b32_e32 v228, 0xffff0000, v107
	v_mul_f32_e32 v221, v38, v221
	v_fma_f32 v221, v54, v223, v221
	v_mul_f32_e32 v225, v70, v225
	v_add_f32_e32 v221, v221, v225
	v_mul_f32_e32 v221, v221, v227
	v_mul_f32_e32 v222, v39, v222
	v_fma_f32 v222, v55, v224, v222
	v_mul_f32_e32 v226, v71, v226
	v_add_f32_e32 v222, v222, v226
	v_mul_f32_e32 v222, v222, v228
	v_cvt_pk_bf16_f32 v243, v221, v222
	v_lshlrev_b32_e32 v221, 16, v124
	v_and_b32_e32 v222, 0xffff0000, v124
	v_lshlrev_b32_e32 v223, 16, v116
	v_and_b32_e32 v224, 0xffff0000, v116
	v_lshlrev_b32_e32 v225, 16, v132
	v_and_b32_e32 v226, 0xffff0000, v132
	v_lshlrev_b32_e32 v227, 16, v108
	v_and_b32_e32 v228, 0xffff0000, v108
	v_mul_f32_e32 v221, v40, v221
	v_fma_f32 v221, v56, v223, v221
	v_mul_f32_e32 v225, v72, v225
	v_add_f32_e32 v221, v221, v225
	v_mul_f32_e32 v221, v221, v227
	v_mul_f32_e32 v222, v41, v222
	v_fma_f32 v222, v57, v224, v222
	v_mul_f32_e32 v226, v73, v226
	v_add_f32_e32 v222, v222, v226
	v_mul_f32_e32 v222, v222, v228
	v_cvt_pk_bf16_f32 v244, v221, v222
	v_lshlrev_b32_e32 v221, 16, v125
	v_and_b32_e32 v222, 0xffff0000, v125
	v_lshlrev_b32_e32 v223, 16, v117
	v_and_b32_e32 v224, 0xffff0000, v117
	v_lshlrev_b32_e32 v225, 16, v133
	v_and_b32_e32 v226, 0xffff0000, v133
	v_lshlrev_b32_e32 v227, 16, v109
	v_and_b32_e32 v228, 0xffff0000, v109
	v_mul_f32_e32 v221, v42, v221
	v_fma_f32 v221, v58, v223, v221
	v_mul_f32_e32 v225, v74, v225
	v_add_f32_e32 v221, v221, v225
	v_mul_f32_e32 v221, v221, v227
	v_mul_f32_e32 v222, v43, v222
	v_fma_f32 v222, v59, v224, v222
	v_mul_f32_e32 v226, v75, v226
	v_add_f32_e32 v222, v222, v226
	v_mul_f32_e32 v222, v222, v228
	v_cvt_pk_bf16_f32 v245, v221, v222
	v_lshlrev_b32_e32 v221, 16, v126
	v_and_b32_e32 v222, 0xffff0000, v126
	v_lshlrev_b32_e32 v223, 16, v118
	v_and_b32_e32 v224, 0xffff0000, v118
	v_lshlrev_b32_e32 v225, 16, v134
	v_and_b32_e32 v226, 0xffff0000, v134
	v_lshlrev_b32_e32 v227, 16, v110
	v_and_b32_e32 v228, 0xffff0000, v110
	v_mul_f32_e32 v221, v44, v221
	v_fma_f32 v221, v60, v223, v221
	v_mul_f32_e32 v225, v76, v225
	v_add_f32_e32 v221, v221, v225
	v_mul_f32_e32 v221, v221, v227
	v_mul_f32_e32 v222, v45, v222
	v_fma_f32 v222, v61, v224, v222
	v_mul_f32_e32 v226, v77, v226
	v_add_f32_e32 v222, v222, v226
	v_mul_f32_e32 v222, v222, v228
	v_cvt_pk_bf16_f32 v246, v221, v222
	v_lshlrev_b32_e32 v221, 16, v127
	v_and_b32_e32 v222, 0xffff0000, v127
	v_lshlrev_b32_e32 v223, 16, v119
	v_and_b32_e32 v224, 0xffff0000, v119
	v_lshlrev_b32_e32 v225, 16, v135
	v_and_b32_e32 v226, 0xffff0000, v135
	v_lshlrev_b32_e32 v227, 16, v111
	v_and_b32_e32 v228, 0xffff0000, v111
	v_mul_f32_e32 v221, v46, v221
	v_fma_f32 v221, v62, v223, v221
	v_mul_f32_e32 v225, v78, v225
	v_add_f32_e32 v221, v221, v225
	v_mul_f32_e32 v221, v221, v227
	v_mul_f32_e32 v222, v47, v222
	v_fma_f32 v222, v63, v224, v222
	v_mul_f32_e32 v226, v79, v226
	v_add_f32_e32 v222, v222, v226
	v_mul_f32_e32 v222, v222, v228
	v_cvt_pk_bf16_f32 v247, v221, v222
	global_store_dwordx4 v0, v[240:243], s[24:25] offset:2048
	global_store_dwordx4 v0, v[244:247], s[24:25] offset:2064
	s_add_u32 s24, s24, s26
	s_addc_u32 s25, s25, s27
	s_branch .Lcb_done
.Lcb_last_b:
	s_waitcnt vmcnt(0)
	s_cmp_lg_u32 s4, 0
	s_cbranch_scc1 .Lcb_hp_bl
	v_mov_b32_e32 v186, 0
	v_mov_b32_e32 v187, 0
	v_mov_b32_e32 v188, 0
	v_mov_b32_e32 v189, 0
	v_mov_b32_e32 v190, 0
	v_mov_b32_e32 v191, 0
	v_mov_b32_e32 v192, 0
	v_mov_b32_e32 v193, 0

.Lcb_hn_bl:
	v_lshlrev_b32_e32 v221, 16, v136
	v_lshlrev_b32_e32 v222, 16, v144
	v_and_b32_e32 v223, 0xffff0000, v136
	v_and_b32_e32 v224, 0xffff0000, v144
	v_add_f32_e32 v205, v222, v221
	v_add_f32_e32 v206, v224, v223
	v_lshlrev_b32_e32 v221, 16, v137
	v_lshlrev_b32_e32 v222, 16, v145
	v_and_b32_e32 v223, 0xffff0000, v137
	v_and_b32_e32 v224, 0xffff0000, v145
	v_add_f32_e32 v207, v222, v221
	v_add_f32_e32 v208, v224, v223
	v_lshlrev_b32_e32 v221, 16, v138
	v_lshlrev_b32_e32 v222, 16, v146
	v_and_b32_e32 v223, 0xffff0000, v138
	v_and_b32_e32 v224, 0xffff0000, v146
	v_add_f32_e32 v209, v222, v221
	v_add_f32_e32 v210, v224, v223
	v_lshlrev_b32_e32 v221, 16, v139
	v_lshlrev_b32_e32 v222, 16, v147
	v_and_b32_e32 v223, 0xffff0000, v139
	v_and_b32_e32 v224, 0xffff0000, v147
	v_add_f32_e32 v211, v222, v221
	v_add_f32_e32 v212, v224, v223
	v_lshlrev_b32_e32 v221, 16, v140
	v_lshlrev_b32_e32 v222, 16, v148
	v_and_b32_e32 v223, 0xffff0000, v140
	v_and_b32_e32 v224, 0xffff0000, v148
	v_add_f32_e32 v213, v222, v221
	v_add_f32_e32 v214, v224, v223
	v_lshlrev_b32_e32 v221, 16, v141
	v_lshlrev_b32_e32 v222, 16, v149
	v_and_b32_e32 v223, 0xffff0000, v141
	v_and_b32_e32 v224, 0xffff0000, v149
	v_add_f32_e32 v215, v222, v221
	v_add_f32_e32 v216, v224, v223
	v_lshlrev_b32_e32 v221, 16, v142
	v_lshlrev_b32_e32 v222, 16, v150
	v_and_b32_e32 v223, 0xffff0000, v142
	v_and_b32_e32 v224, 0xffff0000, v150
	v_add_f32_e32 v217, v222, v221
	v_add_f32_e32 v218, v224, v223
	v_lshlrev_b32_e32 v221, 16, v143
	v_lshlrev_b32_e32 v222, 16, v151
	v_and_b32_e32 v223, 0xffff0000, v143
	v_and_b32_e32 v224, 0xffff0000, v151
	v_add_f32_e32 v219, v222, v221
	v_add_f32_e32 v220, v224, v223
	v_mul_f32_e32 v229, v205, v205
	v_fmac_f32_e32 v229, v206, v206
	v_fmac_f32_e32 v229, v207, v207
	v_fmac_f32_e32 v229, v208, v208
	v_fmac_f32_e32 v229, v209, v209
	v_fmac_f32_e32 v229, v210, v210
	v_fmac_f32_e32 v229, v211, v211
	v_fmac_f32_e32 v229, v212, v212
	v_fmac_f32_e32 v229, v213, v213
	v_fmac_f32_e32 v229, v214, v214
	v_fmac_f32_e32 v229, v215, v215
	v_fmac_f32_e32 v229, v216, v216
	v_fmac_f32_e32 v229, v217, v217
	v_fmac_f32_e32 v229, v218, v218
	v_fmac_f32_e32 v229, v219, v219
	v_fmac_f32_e32 v229, v220, v220
	ds_bpermute_b32 v231, v9, v229
	s_waitcnt lgkmcnt(0)
	v_add_f32_e32 v229, v229, v231
	ds_bpermute_b32 v231, v10, v229
	s_waitcnt lgkmcnt(0)
	v_add_f32_e32 v229, v229, v231
	ds_bpermute_b32 v231, v11, v229
	s_waitcnt lgkmcnt(0)
	v_add_f32_e32 v229, v229, v231
	v_fmamk_f32 v229, v229, 0x3c000000, v195
	v_cmp_gt_f32_e32 vcc, s74, v229
	v_mul_f32_e32 v231, 0x4b800000, v229
	s_nop 1
	v_cndmask_b32_e32 v229, v229, v231, vcc
	v_rsq_f32_e32 v230, v229
	s_nop 0
	v_mul_f32_e32 v231, 0x45800000, v230
	v_cndmask_b32_e32 v230, v230, v231, vcc
	v_lshlrev_b32_e32 v221, 16, v162
	v_and_b32_e32 v222, 0xffff0000, v162
	v_mul_f32_e32 v205, v205, v230
	v_mul_f32_e32 v205, v16, v205
	v_mul_f32_e32 v205, v205, v221
	v_mul_f32_e32 v206, v206, v230
	v_mul_f32_e32 v206, v17, v206
	v_mul_f32_e32 v206, v206, v222
	v_cvt_pk_bf16_f32 v232, v205, v206
	v_lshlrev_b32_e32 v221, 16, v163
	v_and_b32_e32 v222, 0xffff0000, v163
	v_mul_f32_e32 v207, v207, v230
	v_mul_f32_e32 v207, v18, v207
	v_mul_f32_e32 v207, v207, v221
	v_mul_f32_e32 v208, v208, v230
	v_mul_f32_e32 v208, v19, v208
	v_mul_f32_e32 v208, v208, v222
	v_cvt_pk_bf16_f32 v233, v207, v208
	v_lshlrev_b32_e32 v221, 16, v164
	v_and_b32_e32 v222, 0xffff0000, v164
	v_mul_f32_e32 v209, v209, v230
	v_mul_f32_e32 v209, v20, v209
	v_mul_f32_e32 v209, v209, v221
	v_mul_f32_e32 v210, v210, v230
	v_mul_f32_e32 v210, v21, v210
	v_mul_f32_e32 v210, v210, v222
	v_cvt_pk_bf16_f32 v234, v209, v210
	v_lshlrev_b32_e32 v221, 16, v165
	v_and_b32_e32 v222, 0xffff0000, v165
	v_mul_f32_e32 v211, v211, v230
	v_mul_f32_e32 v211, v22, v211
	v_mul_f32_e32 v211, v211, v221
	v_mul_f32_e32 v212, v212, v230
	v_mul_f32_e32 v212, v23, v212
	v_mul_f32_e32 v212, v212, v222
	v_cvt_pk_bf16_f32 v235, v211, v212
	v_lshlrev_b32_e32 v221, 16, v166
	v_and_b32_e32 v222, 0xffff0000, v166
	v_mul_f32_e32 v213, v213, v230
	v_mul_f32_e32 v213, v24, v213
	v_mul_f32_e32 v213, v213, v221
	v_mul_f32_e32 v214, v214, v230
	v_mul_f32_e32 v214, v25, v214
	v_mul_f32_e32 v214, v214, v222
	v_cvt_pk_bf16_f32 v236, v213, v214
	v_lshlrev_b32_e32 v221, 16, v167
	v_and_b32_e32 v222, 0xffff0000, v167
	v_mul_f32_e32 v215, v215, v230
	v_mul_f32_e32 v215, v26, v215
	v_mul_f32_e32 v215, v215, v221
	v_mul_f32_e32 v216, v216, v230
	v_mul_f32_e32 v216, v27, v216
	v_mul_f32_e32 v216, v216, v222
	v_cvt_pk_bf16_f32 v237, v215, v216
	v_lshlrev_b32_e32 v221, 16, v168
	v_and_b32_e32 v222, 0xffff0000, v168
	v_mul_f32_e32 v217, v217, v230
	v_mul_f32_e32 v217, v28, v217
	v_mul_f32_e32 v217, v217, v221
	v_mul_f32_e32 v218, v218, v230
	v_mul_f32_e32 v218, v29, v218
	v_mul_f32_e32 v218, v218, v222
	v_cvt_pk_bf16_f32 v238, v217, v218
	v_lshlrev_b32_e32 v221, 16, v169
	v_and_b32_e32 v222, 0xffff0000, v169
	v_mul_f32_e32 v219, v219, v230
	v_mul_f32_e32 v219, v30, v219
	v_mul_f32_e32 v219, v219, v221
	v_mul_f32_e32 v220, v220, v230
	v_mul_f32_e32 v220, v31, v220
	v_mul_f32_e32 v220, v220, v222
	v_cvt_pk_bf16_f32 v239, v219, v220
	global_store_dwordx4 v0, v[232:235], s[24:25]
	global_store_dwordx4 v0, v[236:239], s[24:25] offset:16
	v_lshlrev_b32_e32 v221, 16, v186
	v_and_b32_e32 v222, 0xffff0000, v186
	v_lshlrev_b32_e32 v223, 16, v178
	v_and_b32_e32 v224, 0xffff0000, v178
	v_lshlrev_b32_e32 v225, 16, v12
	v_and_b32_e32 v226, 0xffff0000, v12
	v_lshlrev_b32_e32 v227, 16, v170
	v_and_b32_e32 v228, 0xffff0000, v170
	v_mul_f32_e32 v221, v32, v221
	v_fma_f32 v221, v48, v223, v221
	v_mul_f32_e32 v225, v64, v225
	v_add_f32_e32 v221, v221, v225
	v_mul_f32_e32 v221, v221, v227
	v_mul_f32_e32 v222, v33, v222
	v_fma_f32 v222, v49, v224, v222
	v_mul_f32_e32 v226, v65, v226
	v_add_f32_e32 v222, v222, v226
	v_mul_f32_e32 v222, v222, v228
	v_cvt_pk_bf16_f32 v240, v221, v222
	v_lshlrev_b32_e32 v221, 16, v187
	v_and_b32_e32 v222, 0xffff0000, v187
	v_lshlrev_b32_e32 v223, 16, v179
	v_and_b32_e32 v224, 0xffff0000, v179
	v_lshlrev_b32_e32 v225, 16, v13
	v_and_b32_e32 v226, 0xffff0000, v13
	v_lshlrev_b32_e32 v227, 16, v171
	v_and_b32_e32 v228, 0xffff0000, v171
	v_mul_f32_e32 v221, v34, v221
	v_fma_f32 v221, v50, v223, v221
	v_mul_f32_e32 v225, v66, v225
	v_add_f32_e32 v221, v221, v225
	v_mul_f32_e32 v221, v221, v227
	v_mul_f32_e32 v222, v35, v222
	v_fma_f32 v222, v51, v224, v222
	v_mul_f32_e32 v226, v67, v226
	v_add_f32_e32 v222, v222, v226
	v_mul_f32_e32 v222, v222, v228
	v_cvt_pk_bf16_f32 v241, v221, v222
	v_lshlrev_b32_e32 v221, 16, v188
	v_and_b32_e32 v222, 0xffff0000, v188
	v_lshlrev_b32_e32 v223, 16, v180
	v_and_b32_e32 v224, 0xffff0000, v180
	v_lshlrev_b32_e32 v225, 16, v14
	v_and_b32_e32 v226, 0xffff0000, v14
	v_lshlrev_b32_e32 v227, 16, v172
	v_and_b32_e32 v228, 0xffff0000, v172
	v_mul_f32_e32 v221, v36, v221
	v_fma_f32 v221, v52, v223, v221
	v_mul_f32_e32 v225, v68, v225
	v_add_f32_e32 v221, v221, v225
	v_mul_f32_e32 v221, v221, v227
	v_mul_f32_e32 v222, v37, v222
	v_fma_f32 v222, v53, v224, v222
	v_mul_f32_e32 v226, v69, v226
	v_add_f32_e32 v222, v222, v226
	v_mul_f32_e32 v222, v222, v228
	v_cvt_pk_bf16_f32 v242, v221, v222
	v_lshlrev_b32_e32 v221, 16, v189
	v_and_b32_e32 v222, 0xffff0000, v189
	v_lshlrev_b32_e32 v223, 16, v181
	v_and_b32_e32 v224, 0xffff0000, v181
	v_lshlrev_b32_e32 v225, 16, v15
	v_and_b32_e32 v226, 0xffff0000, v15
	v_lshlrev_b32_e32 v227, 16, v173
	v_and_b32_e32 v228, 0xffff0000, v173
	v_mul_f32_e32 v221, v38, v221
	v_fma_f32 v221, v54, v223, v221
	v_mul_f32_e32 v225, v70, v225
	v_add_f32_e32 v221, v221, v225
	v_mul_f32_e32 v221, v221, v227
	v_mul_f32_e32 v222, v39, v222
	v_fma_f32 v222, v55, v224, v222
	v_mul_f32_e32 v226, v71, v226
	v_add_f32_e32 v222, v222, v226
	v_mul_f32_e32 v222, v222, v228
	v_cvt_pk_bf16_f32 v243, v221, v222
	v_lshlrev_b32_e32 v221, 16, v190
	v_and_b32_e32 v222, 0xffff0000, v190
	v_lshlrev_b32_e32 v223, 16, v182
	v_and_b32_e32 v224, 0xffff0000, v182
	v_lshlrev_b32_e32 v225, 16, v248
	v_and_b32_e32 v226, 0xffff0000, v248
	v_lshlrev_b32_e32 v227, 16, v174
	v_and_b32_e32 v228, 0xffff0000, v174
	v_mul_f32_e32 v221, v40, v221
	v_fma_f32 v221, v56, v223, v221
	v_mul_f32_e32 v225, v72, v225
	v_add_f32_e32 v221, v221, v225
	v_mul_f32_e32 v221, v221, v227
	v_mul_f32_e32 v222, v41, v222
	v_fma_f32 v222, v57, v224, v222
	v_mul_f32_e32 v226, v73, v226
	v_add_f32_e32 v222, v222, v226
	v_mul_f32_e32 v222, v222, v228
	v_cvt_pk_bf16_f32 v244, v221, v222
	v_lshlrev_b32_e32 v221, 16, v191
	v_and_b32_e32 v222, 0xffff0000, v191
	v_lshlrev_b32_e32 v223, 16, v183
	v_and_b32_e32 v224, 0xffff0000, v183
	v_lshlrev_b32_e32 v225, 16, v249
	v_and_b32_e32 v226, 0xffff0000, v249
	v_lshlrev_b32_e32 v227, 16, v175
	v_and_b32_e32 v228, 0xffff0000, v175
	v_mul_f32_e32 v221, v42, v221
	v_fma_f32 v221, v58, v223, v221
	v_mul_f32_e32 v225, v74, v225
	v_add_f32_e32 v221, v221, v225
	v_mul_f32_e32 v221, v221, v227
	v_mul_f32_e32 v222, v43, v222
	v_fma_f32 v222, v59, v224, v222
	v_mul_f32_e32 v226, v75, v226
	v_add_f32_e32 v222, v222, v226
	v_mul_f32_e32 v222, v222, v228
	v_cvt_pk_bf16_f32 v245, v221, v222
	v_lshlrev_b32_e32 v221, 16, v192
	v_and_b32_e32 v222, 0xffff0000, v192
	v_lshlrev_b32_e32 v223, 16, v184
	v_and_b32_e32 v224, 0xffff0000, v184
	v_lshlrev_b32_e32 v225, 16, v250
	v_and_b32_e32 v226, 0xffff0000, v250
	v_lshlrev_b32_e32 v227, 16, v176
	v_and_b32_e32 v228, 0xffff0000, v176
	v_mul_f32_e32 v221, v44, v221
	v_fma_f32 v221, v60, v223, v221
	v_mul_f32_e32 v225, v76, v225
	v_add_f32_e32 v221, v221, v225
	v_mul_f32_e32 v221, v221, v227
	v_mul_f32_e32 v222, v45, v222
	v_fma_f32 v222, v61, v224, v222
	v_mul_f32_e32 v226, v77, v226
	v_add_f32_e32 v222, v222, v226
	v_mul_f32_e32 v222, v222, v228
	v_cvt_pk_bf16_f32 v246, v221, v222
	v_lshlrev_b32_e32 v221, 16, v193
	v_and_b32_e32 v222, 0xffff0000, v193
	v_lshlrev_b32_e32 v223, 16, v185
	v_and_b32_e32 v224, 0xffff0000, v185
	v_lshlrev_b32_e32 v225, 16, v251
	v_and_b32_e32 v226, 0xffff0000, v251
	v_lshlrev_b32_e32 v227, 16, v177
	v_and_b32_e32 v228, 0xffff0000, v177
	v_mul_f32_e32 v221, v46, v221
	v_fma_f32 v221, v62, v223, v221
	v_mul_f32_e32 v225, v78, v225
	v_add_f32_e32 v221, v221, v225
	v_mul_f32_e32 v221, v221, v227
	v_mul_f32_e32 v222, v47, v222
	v_fma_f32 v222, v63, v224, v222
	v_mul_f32_e32 v226, v79, v226
	v_add_f32_e32 v222, v222, v226
	v_mul_f32_e32 v222, v222, v228
	v_cvt_pk_bf16_f32 v247, v221, v222
	global_store_dwordx4 v0, v[240:243], s[24:25] offset:2048
	global_store_dwordx4 v0, v[244:247], s[24:25] offset:2064
	s_add_u32 s24, s24, s26
	s_addc_u32 s25, s25, s27
.Lcb_done:
.LBB0_499:
	s_load_dword s0, s[0:1], 0x9c
	s_mul_i32 s1, s80, 9
	s_add_i32 s4, s1, 7
	s_waitcnt lgkmcnt(0)
	s_cmp_ge_i32 s4, s0
	s_cbranch_scc1 .LBB0_511
	s_waitcnt vmcnt(0)
	s_waitcnt vmcnt(0)
	s_barrier
	s_and_saveexec_b64 s[0:1], s[90:91]
	v_readlane_b32 s34, v253, 45
	v_readlane_b32 s35, v253, 46
	s_cbranch_execz .LBB0_549
	v_readlane_b32 s5, v253, 35
	s_waitcnt vmcnt(0) expcnt(0) lgkmcnt(0)
	s_nop 0
	v_mov_b32_e32 v0, s5
	ds_read_b32 v2, v0
	v_readlane_b32 s5, v253, 36
	s_waitcnt lgkmcnt(0)
	v_cmp_ne_u32_e32 vcc, 0, v2
	v_mov_b32_e32 v0, s5
	ds_read_b32 v0, v0
	s_cbranch_vccnz .LBB0_517
	s_mov_b32 s5, 1
	s_branch .LBB0_504
